# attention tile loop hand-rescheduled: exp/rowsum/pack of map0 split across QK and PV segments, lazy rescale path, masked tiles skipped, fewer VALU
# speedup vs baseline: 1.0168x; 1.0168x over previous
; DI void dattn_unit2(const bf16_t* __restrict__ Qg, const bf16_t* __restrict__ Kg, const bf16_t* __restrict__ Vg, bf16_t* __restrict__ Og,
;                     int ntiles, int wave_tiles, float lam, const float* __restrict__ gsub, lds_t* shm) {
;     ...
;   for (int kt = 0; kt < ntiles; ++kt) {
;     const int slot2 = slot >= 1 ? slot - 1 : 2;
;     issueK(kt + 2, slot2);
;     const float msk = (kt < wave_tiles) ? 0.f : -INFINITY;
;     const unsigned so = slot * 16384;
;     lds_t* K0 = shm + (so + ka0); lds_t* K2 = shm + (so + ka2);
;     bf16x8 P[2][2][2]; float alpha[2]; bool resc[2];
; #pragma unroll
;     for (int m = 0; m < 2; ++m) {
;       f32x16 s[2];
; #pragma unroll
;       for (int kb = 0; kb < 2; ++kb)
; #pragma unroll
;         for (int i = 0; i < 16; ++i) s[kb][i] = 0.f;
; #pragma unroll
;       for (int ss = 0; ss < 4; ++ss) {
;         const bf16x8 qv = *LDSP(const bf16x8, Qst + ((ss & 1) ? ka2 : ka0) + 512 * (ss >> 1) + 1024 * m);
; #pragma unroll
;         for (int kb = 0; kb < 2; ++kb) {
;           const bf16x8 kf = *LDSP(const bf16x8, ((ss & 1) ? K2 : K0) + kb * 8192 + 512 * (ss >> 1) + 1024 * m);
;           s[kb] = MFMA32(kf, qv, s[kb]);
;         }
;       }
;       float mx = s[0][0];
; #pragma unroll
;       for (int i = 1; i < 16; ++i) mx = fmaxf(mx, s[0][i]);
; #pragma unroll
;       for (int i = 0; i < 16; ++i) mx = fmaxf(mx, s[1][i]);
;       { const auto sw = __builtin_amdgcn_permlane32_swap(__float_as_uint(mx), __float_as_uint(mx), false, false); mx = fmaxf(__uint_as_float(sw[0]), __uint_as_float(sw[1])) + msk; }
;       resc[m] = __builtin_amdgcn_ballot_w64(mx > mrun[m] + 8.0f) != 0;
;       alpha[m] = 1.0f;
;       if (resc[m]) { const float mnew = fmaxf(mrun[m], mx); alpha[m] = __builtin_amdgcn_exp2f(mrun[m] - mnew); mrun[m] = mnew; lrun[m] *= alpha[m]; }
;       const float msub = mrun[m] - msk;
;       float rs = 0.f;
; #pragma unroll
;       for (int kb = 0; kb < 2; ++kb)
; #pragma unroll
;         for (int s2 = 0; s2 < 2; ++s2) {
;           float e[8];
; #pragma unroll
;           for (int j = 0; j < 8; ++j) { e[j] = __builtin_amdgcn_exp2f(s[kb][8 * s2 + j] - msub); rs += e[j]; }
;           u32x4 w; w.x = pk2(e[0], e[1]); w.y = pk2(e[2], e[3]); w.z = pk2(e[4], e[5]); w.w = pk2(e[6], e[7]);
;           P[m][kb][s2] = __builtin_bit_cast(bf16x8, w);
;           __builtin_amdgcn_sched_barrier(0);
;         }
.LBB0_419:
	s_add_i32 s4, s60, 2
	s_lshl_b32 s6, s59, 14
	s_min_i32 s4, s4, s55
	s_add_i32 s5, s6, 0xffffc000
	s_cmp_gt_i32 s59, 0
	s_cselect_b32 s5, s5, 0x8000
	s_add_i32 s62, s53, s5
	s_lshl_b32 s63, s4, 17
	s_add_u32 s4, s8, s63
	s_addc_u32 s5, s9, 0
	s_mov_b32 m0, s62
	s_add_i32 s61, s6, 0
	global_load_lds_dwordx4 v192, s[4:5]
	s_add_i32 m0, s62, 0x2000
	s_cmp_gt_i32 s60, s54
	global_load_lds_dwordx4 v196, s[4:5]
	s_cbranch_scc1 .Lda_maskA
	v_add_u32_e32 v202, s61, v218
	v_add_u32_e32 v242, s52, v219
	ds_read_b128 v[128:131], v202
	ds_read_b128 v[132:135], v225
	ds_read_b128 v[144:147], v225 offset:512
	ds_read_b128 v[148:151], v202 offset:512
	v_add_u32_e32 v207, s61, v219
	s_waitcnt lgkmcnt(0)
	v_mfma_f32_32x32x16_bf16 v[160:175], v[128:131], v[132:135], 0
	ds_read_b128 v[128:131], v202 offset:8192
	ds_read_b128 v[152:155], v202 offset:8704
	ds_read_b128 v[156:159], v207
	ds_read_b128 v[176:179], v242
	ds_read_b128 v[180:183], v242 offset:512
	ds_read_b128 v[184:187], v207 offset:512
	s_waitcnt lgkmcnt(0)
	v_mfma_f32_32x32x16_bf16 v[160:175], v[156:159], v[176:179], v[160:175]
	ds_read_b128 v[156:159], v207 offset:8192
	ds_read_b128 v[188:191], v207 offset:8704
	v_mfma_f32_32x32x16_bf16 v[128:143], v[128:131], v[132:135], 0
	v_mfma_f32_32x32x16_bf16 v[160:175], v[148:151], v[144:147], v[160:175]
	s_waitcnt lgkmcnt(0)
	v_mfma_f32_32x32x16_bf16 v[128:143], v[156:159], v[176:179], v[128:143]
	v_mfma_f32_32x32x16_bf16 v[160:175], v[184:187], v[180:183], v[160:175]
	v_mfma_f32_32x32x16_bf16 v[128:143], v[152:155], v[144:147], v[128:143]
	s_nop 10
	v_max3_f32 v144, v160, v161, v162
	v_max3_f32 v144, v144, v163, v164
	v_max3_f32 v144, v144, v165, v166
	v_max3_f32 v144, v144, v167, v168
	v_mfma_f32_32x32x16_bf16 v[128:143], v[188:191], v[180:183], v[128:143]
	v_max3_f32 v144, v144, v169, v170
	v_max3_f32 v144, v144, v171, v172
	v_max3_f32 v144, v144, v173, v174
	v_max_f32_e32 v144, v144, v175
	s_nop 8
	v_max3_f32 v144, v144, v128, v129
	v_max3_f32 v144, v144, v130, v131
	v_max3_f32 v144, v144, v132, v133
	v_max3_f32 v144, v144, v134, v135
	v_max3_f32 v144, v144, v136, v137
	v_max3_f32 v144, v144, v138, v139
	v_max3_f32 v144, v144, v140, v141
	v_max3_f32 v144, v144, v142, v143
	v_mov_b32_e32 v145, v144
	s_nop 1
	v_permlane32_swap_b32_e32 v144, v145
	v_max_f32_e32 v206, v144, v145
	v_sub_f32_e32 v146, v206, v199
	v_cmp_lt_f32_e32 vcc, 0x41000000, v146
	s_mov_b64 s[6:7], -1
	ds_read_b128 v[144:147], v202 offset:1024
	ds_read_b128 v[148:151], v225 offset:1024
	ds_read_b128 v[208:211], v225 offset:1536
	ds_read_b128 v[226:229], v202 offset:1536
	s_cmp_eq_u64 vcc, 0
	s_cbranch_scc1 .Lda_nr0
	v_max_f32_e32 v206, v199, v206
	v_sub_f32_e32 v205, v199, v206
	v_mov_b32_e32 v199, v206
	v_exp_f32_e32 v203, v205
	s_mov_b64 s[6:7], 0
	s_nop 0
	v_mul_f32_e32 v201, v201, v203
.Lda_nr0:
	v_sub_f32_e32 v160, v160, v199
	v_sub_f32_e32 v161, v161, v199
	v_sub_f32_e32 v162, v162, v199
	v_exp_f32_e32 v160, v160
	v_sub_f32_e32 v163, v163, v199
	v_exp_f32_e32 v161, v161
	v_sub_f32_e32 v164, v164, v199
	v_exp_f32_e32 v162, v162
	v_sub_f32_e32 v165, v165, v199
	v_exp_f32_e32 v163, v163
	s_waitcnt lgkmcnt(0)
	v_mfma_f32_32x32x16_bf16 v[176:191], v[144:147], v[148:151], 0
	ds_read_b128 v[144:147], v202 offset:9216
	ds_read_b128 v[230:233], v202 offset:9728
	ds_read_b128 v[234:237], v207 offset:1024
	ds_read_b128 v[238:241], v242 offset:1024
	ds_read_b128 v[242:245], v242 offset:1536
	ds_read_b128 v[246:249], v207 offset:1536
	v_add_f32_e32 v201, v201, v160
	v_sub_f32_e32 v166, v166, v199
	v_exp_f32_e32 v164, v164
	v_add_f32_e32 v201, v201, v161
	v_sub_f32_e32 v167, v167, v199
	v_cvt_pk_bf16_f32 v160, v160, v161
	v_exp_f32_e32 v165, v165
	v_add_f32_e32 v201, v201, v162
	v_sub_f32_e32 v168, v168, v199
	v_exp_f32_e32 v166, v166
	v_add_f32_e32 v201, v201, v163
	v_sub_f32_e32 v169, v169, v199
	s_waitcnt lgkmcnt(0)
	v_mfma_f32_32x32x16_bf16 v[176:191], v[234:237], v[238:241], v[176:191]
	ds_read_b128 v[234:237], v207 offset:9216
	ds_read_b128 v[250:253], v207 offset:9728
	v_cvt_pk_bf16_f32 v161, v162, v163
	v_exp_f32_e32 v167, v167
	v_add_f32_e32 v201, v201, v164
	v_mfma_f32_32x32x16_bf16 v[144:159], v[144:147], v[148:151], 0
	v_sub_f32_e32 v170, v170, v199
	v_exp_f32_e32 v168, v168
	v_add_f32_e32 v201, v201, v165
	v_sub_f32_e32 v171, v171, v199
	v_cvt_pk_bf16_f32 v162, v164, v165
	v_mfma_f32_32x32x16_bf16 v[176:191], v[226:229], v[208:211], v[176:191]
	v_exp_f32_e32 v169, v169
	v_add_f32_e32 v201, v201, v166
	v_sub_f32_e32 v172, v172, v199
	v_exp_f32_e32 v170, v170
	v_add_f32_e32 v201, v201, v167
	s_waitcnt lgkmcnt(0)
	v_mfma_f32_32x32x16_bf16 v[144:159], v[234:237], v[238:241], v[144:159]
	v_sub_f32_e32 v173, v173, v199
	v_cvt_pk_bf16_f32 v163, v166, v167
	v_exp_f32_e32 v171, v171
	v_add_f32_e32 v201, v201, v168
	v_sub_f32_e32 v174, v174, v199
	v_mfma_f32_32x32x16_bf16 v[176:191], v[246:249], v[242:245], v[176:191]
	v_exp_f32_e32 v172, v172
	v_add_f32_e32 v201, v201, v169
	v_sub_f32_e32 v175, v175, v199
	v_cvt_pk_bf16_f32 v164, v168, v169
	v_exp_f32_e32 v173, v173
	v_mfma_f32_32x32x16_bf16 v[144:159], v[230:233], v[208:211], v[144:159]
	v_add_f32_e32 v201, v201, v170
	v_exp_f32_e32 v174, v174
	v_add_f32_e32 v201, v201, v171
	v_cvt_pk_bf16_f32 v165, v170, v171
	v_exp_f32_e32 v175, v175
	v_mfma_f32_32x32x16_bf16 v[144:159], v[250:253], v[242:245], v[144:159]
	v_max3_f32 v194, v176, v177, v178
	v_add_f32_e32 v201, v201, v172
	v_add_f32_e32 v201, v201, v173
	v_max3_f32 v194, v194, v179, v180
	v_cvt_pk_bf16_f32 v166, v172, v173
	v_add_f32_e32 v201, v201, v174
	v_max3_f32 v194, v194, v181, v182
	v_add_f32_e32 v201, v201, v175
	v_cvt_pk_bf16_f32 v167, v174, v175
	v_max3_f32 v194, v194, v183, v184
	v_max3_f32 v194, v194, v185, v186
	v_max3_f32 v194, v194, v187, v188
	v_max3_f32 v194, v194, v189, v190
	v_max_f32_e32 v194, v194, v191
	v_max3_f32 v194, v194, v144, v145
	v_max3_f32 v194, v194, v146, v147
	v_max3_f32 v194, v194, v148, v149
	v_max3_f32 v194, v194, v150, v151
	v_max3_f32 v194, v194, v152, v153
	v_max3_f32 v194, v194, v154, v155
	v_max3_f32 v194, v194, v156, v157
	v_max3_f32 v194, v194, v158, v159
	v_mov_b32_e32 v202, v194
	s_nop 1
	v_permlane32_swap_b32_e32 v194, v202
	v_max_f32_e32 v207, v194, v202
	v_sub_f32_e32 v194, v207, v198
	v_cmp_gt_f32_e64 s[4:5], v194, v195
	s_nop 0
	s_cmp_eq_u64 s[4:5], 0
	s_mov_b64 s[4:5], -1
	s_cbranch_scc1 .Lda_nr1
	v_max_f32_e32 v207, v198, v207
	v_sub_f32_e32 v205, v198, v207
	v_mov_b32_e32 v198, v207
	v_exp_f32_e32 v202, v205
	s_mov_b64 s[4:5], 0
	s_nop 0
	v_mul_f32_e32 v200, v200, v202
; #define WAIT_V(n) asm volatile("s_waitcnt vmcnt(" #n ")" ::: "memory")
; #define BAR __builtin_amdgcn_s_barrier()
; #define WAIT_V(n) asm volatile("s_waitcnt vmcnt(" #n ")" ::: "memory")
; #define BAR do { __builtin_amdgcn_sched_barrier(0); __builtin_amdgcn_s_barrier(); asm volatile("" ::: "memory"); __builtin_amdgcn_sched_barrier(0); } while (0)
; DI void dattn_unit2(const bf16_t* __restrict__ Qg, const bf16_t* __restrict__ Kg, const bf16_t* __restrict__ Vg, bf16_t* __restrict__ Og,
;                     int ntiles, int wave_tiles, float lam, const float* __restrict__ gsub, lds_t* shm) {
;     ...
;     WAIT_V(4); BAR;
;     issueV(kt + 2, slot2);
;     lds_t* V0 = shm + (so + va0); lds_t* V1 = shm + (so + va1);
; #pragma unroll
;     for (int m = 0; m < 2; ++m)
;       if (resc[m]) {
; #pragma unroll
;         for (int c = 0; c < NC; ++c) O[m][c] = O[m][c] * alpha[m];
;       }
; #pragma unroll
;     for (int ks = 0; ks < 4; ++ks) {
;       bf16x8 vf[NC];
; #pragma unroll
;       for (int c = 0; c < NC; ++c) { const int vo = 512 * c + 4096 * ks; vf[c] = tr_pair(V0 + vo, V1 + vo + 2048); }
.Lda_nr1:
.Lda_w1:
	s_waitcnt vmcnt(4)
	s_barrier
	s_setprio 1
	s_add_i32 m0, s62, 0xc000
	s_add_u32 s64, s28, s63
	s_addc_u32 s65, s29, 0
	global_load_lds_dwordx4 v192, s[64:65]
	s_add_i32 m0, s62, 0xe000
	s_cmp_gt_i32 s60, s54
	global_load_lds_dwordx4 v196, s[64:65]
	s_cbranch_scc1 .Lda_w2
	v_add3_u32 v194, s61, v220, v221
	v_add3_u32 v204, v194, v222, v223
	v_add3_u32 v205, v194, v224, v223
	ds_read_b64_tr_b16 v[226:227], v204 offset:49152
	ds_read_b64_tr_b16 v[228:229], v205 offset:51200
	ds_read_b64_tr_b16 v[230:231], v204 offset:49664
	ds_read_b64_tr_b16 v[232:233], v205 offset:51712
	ds_read_b64_tr_b16 v[234:235], v204 offset:50176
	ds_read_b64_tr_b16 v[236:237], v205 offset:52224
	ds_read_b64_tr_b16 v[238:239], v204 offset:50688
	ds_read_b64_tr_b16 v[240:241], v205 offset:52736
	s_and_b64 vcc, exec, s[6:7]
	s_cbranch_vccnz .Lda_skip0
	v_pk_mul_f32 v[96:97], v[96:97], v[202:203] op_sel:[0,1]
	v_pk_mul_f32 v[98:99], v[98:99], v[202:203] op_sel:[0,1]
	v_pk_mul_f32 v[100:101], v[100:101], v[202:203] op_sel:[0,1]
	v_pk_mul_f32 v[102:103], v[102:103], v[202:203] op_sel:[0,1]
	v_pk_mul_f32 v[104:105], v[104:105], v[202:203] op_sel:[0,1]
	v_pk_mul_f32 v[106:107], v[106:107], v[202:203] op_sel:[0,1]
	v_pk_mul_f32 v[108:109], v[108:109], v[202:203] op_sel:[0,1]
	v_pk_mul_f32 v[110:111], v[110:111], v[202:203] op_sel:[0,1]
	v_pk_mul_f32 v[64:65], v[64:65], v[202:203] op_sel:[0,1]
	v_pk_mul_f32 v[66:67], v[66:67], v[202:203] op_sel:[0,1]
	v_pk_mul_f32 v[68:69], v[68:69], v[202:203] op_sel:[0,1]
	v_pk_mul_f32 v[70:71], v[70:71], v[202:203] op_sel:[0,1]
	v_pk_mul_f32 v[72:73], v[72:73], v[202:203] op_sel:[0,1]
	v_pk_mul_f32 v[74:75], v[74:75], v[202:203] op_sel:[0,1]
	v_pk_mul_f32 v[76:77], v[76:77], v[202:203] op_sel:[0,1]
	v_pk_mul_f32 v[78:79], v[78:79], v[202:203] op_sel:[0,1]
	v_pk_mul_f32 v[32:33], v[32:33], v[202:203] op_sel:[0,1]
	v_pk_mul_f32 v[34:35], v[34:35], v[202:203] op_sel:[0,1]
	v_pk_mul_f32 v[36:37], v[36:37], v[202:203] op_sel:[0,1]
	v_pk_mul_f32 v[38:39], v[38:39], v[202:203] op_sel:[0,1]
	v_pk_mul_f32 v[40:41], v[40:41], v[202:203] op_sel:[0,1]
	v_pk_mul_f32 v[42:43], v[42:43], v[202:203] op_sel:[0,1]
	v_pk_mul_f32 v[44:45], v[44:45], v[202:203] op_sel:[0,1]
	v_pk_mul_f32 v[46:47], v[46:47], v[202:203] op_sel:[0,1]
	v_pk_mul_f32 v[0:1], v[0:1], v[202:203] op_sel:[0,1]
	v_pk_mul_f32 v[2:3], v[2:3], v[202:203] op_sel:[0,1]
	v_pk_mul_f32 v[4:5], v[4:5], v[202:203] op_sel:[0,1]
	v_pk_mul_f32 v[6:7], v[6:7], v[202:203] op_sel:[0,1]
	v_pk_mul_f32 v[8:9], v[8:9], v[202:203] op_sel:[0,1]
	v_pk_mul_f32 v[10:11], v[10:11], v[202:203] op_sel:[0,1]
	v_pk_mul_f32 v[12:13], v[12:13], v[202:203] op_sel:[0,1]
	v_pk_mul_f32 v[14:15], v[14:15], v[202:203] op_sel:[0,1]
.Lda_skip0:
	s_and_b64 vcc, exec, s[4:5]
	s_cbranch_vccnz .Lda_skip1
	v_pk_mul_f32 v[112:113], v[112:113], v[202:203] op_sel_hi:[1,0]
	v_pk_mul_f32 v[114:115], v[114:115], v[202:203] op_sel_hi:[1,0]
	v_pk_mul_f32 v[116:117], v[116:117], v[202:203] op_sel_hi:[1,0]
	v_pk_mul_f32 v[118:119], v[118:119], v[202:203] op_sel_hi:[1,0]
	v_pk_mul_f32 v[120:121], v[120:121], v[202:203] op_sel_hi:[1,0]
	v_pk_mul_f32 v[122:123], v[122:123], v[202:203] op_sel_hi:[1,0]
	v_pk_mul_f32 v[124:125], v[124:125], v[202:203] op_sel_hi:[1,0]
	v_pk_mul_f32 v[126:127], v[126:127], v[202:203] op_sel_hi:[1,0]
	v_pk_mul_f32 v[80:81], v[80:81], v[202:203] op_sel_hi:[1,0]
	v_pk_mul_f32 v[82:83], v[82:83], v[202:203] op_sel_hi:[1,0]
	v_pk_mul_f32 v[84:85], v[84:85], v[202:203] op_sel_hi:[1,0]
	v_pk_mul_f32 v[86:87], v[86:87], v[202:203] op_sel_hi:[1,0]
	v_pk_mul_f32 v[88:89], v[88:89], v[202:203] op_sel_hi:[1,0]
	v_pk_mul_f32 v[90:91], v[90:91], v[202:203] op_sel_hi:[1,0]
	v_pk_mul_f32 v[92:93], v[92:93], v[202:203] op_sel_hi:[1,0]
	v_pk_mul_f32 v[94:95], v[94:95], v[202:203] op_sel_hi:[1,0]
	v_pk_mul_f32 v[48:49], v[48:49], v[202:203] op_sel_hi:[1,0]
	v_pk_mul_f32 v[50:51], v[50:51], v[202:203] op_sel_hi:[1,0]
	v_pk_mul_f32 v[52:53], v[52:53], v[202:203] op_sel_hi:[1,0]
	v_pk_mul_f32 v[54:55], v[54:55], v[202:203] op_sel_hi:[1,0]
	v_pk_mul_f32 v[56:57], v[56:57], v[202:203] op_sel_hi:[1,0]
	v_pk_mul_f32 v[58:59], v[58:59], v[202:203] op_sel_hi:[1,0]
	v_pk_mul_f32 v[60:61], v[60:61], v[202:203] op_sel_hi:[1,0]
	v_pk_mul_f32 v[62:63], v[62:63], v[202:203] op_sel_hi:[1,0]
	v_pk_mul_f32 v[16:17], v[16:17], v[202:203] op_sel_hi:[1,0]
	v_pk_mul_f32 v[18:19], v[18:19], v[202:203] op_sel_hi:[1,0]
	v_pk_mul_f32 v[20:21], v[20:21], v[202:203] op_sel_hi:[1,0]
	v_pk_mul_f32 v[22:23], v[22:23], v[202:203] op_sel_hi:[1,0]
	v_pk_mul_f32 v[24:25], v[24:25], v[202:203] op_sel_hi:[1,0]
	v_pk_mul_f32 v[26:27], v[26:27], v[202:203] op_sel_hi:[1,0]
	v_pk_mul_f32 v[28:29], v[28:29], v[202:203] op_sel_hi:[1,0]
	v_pk_mul_f32 v[30:31], v[30:31], v[202:203] op_sel_hi:[1,0]
; DI unsigned pk2(float lo, float hi) { bf2_t v = __builtin_convertvector((f32x2){lo, hi}, bf2_t); return __builtin_bit_cast(unsigned, v); }
; #define MFMA32(a, b, c) __builtin_amdgcn_mfma_f32_32x32x16_bf16((a), (b), (c), 0, 0, 0)
; DI void dattn_unit2(const bf16_t* __restrict__ Qg, const bf16_t* __restrict__ Kg, const bf16_t* __restrict__ Vg, bf16_t* __restrict__ Og,
;                     int ntiles, int wave_tiles, float lam, const float* __restrict__ gsub, lds_t* shm) {
;     ...
;       float rs = 0.f;
; #pragma unroll
;       for (int kb = 0; kb < 2; ++kb)
; #pragma unroll
;         for (int s2 = 0; s2 < 2; ++s2) {
;           float e[8];
; #pragma unroll
;           for (int j = 0; j < 8; ++j) { e[j] = __builtin_amdgcn_exp2f(s[kb][8 * s2 + j] - msub); rs += e[j]; }
;           u32x4 w; w.x = pk2(e[0], e[1]); w.y = pk2(e[2], e[3]); w.z = pk2(e[4], e[5]); w.w = pk2(e[6], e[7]);
;           P[m][kb][s2] = __builtin_bit_cast(bf16x8, w);
;           __builtin_amdgcn_sched_barrier(0);
;         }
;     ...
;     for (int ks = 0; ks < 4; ++ks) {
;       bf16x8 vf[NC];
; #pragma unroll
;       for (int c = 0; c < NC; ++c) { const int vo = 512 * c + 4096 * ks; vf[c] = tr_pair(V0 + vo, V1 + vo + 2048); }
; #pragma unroll
;       for (int c = 0; c < NC; ++c) { O[0][c] = MFMA32(vf[c], P[0][ks >> 1][ks & 1], O[0][c]); O[1][c] = MFMA32(vf[c], P[1][ks >> 1][ks & 1], O[1][c]); }
;     }
.Lda_skip1:
	v_sub_f32_e32 v176, v176, v198
	v_sub_f32_e32 v177, v177, v198
	v_sub_f32_e32 v178, v178, v198
	v_exp_f32_e32 v176, v176
	v_sub_f32_e32 v179, v179, v198
	v_exp_f32_e32 v177, v177
	v_sub_f32_e32 v180, v180, v198
	v_exp_f32_e32 v178, v178
	v_sub_f32_e32 v181, v181, v198
	v_exp_f32_e32 v179, v179
	v_add_f32_e32 v200, v200, v176
	v_sub_f32_e32 v182, v182, v198
	v_exp_f32_e32 v180, v180
	v_add_f32_e32 v200, v200, v177
	v_sub_f32_e32 v183, v183, v198
	v_cvt_pk_bf16_f32 v176, v176, v177
	v_exp_f32_e32 v181, v181
	v_add_f32_e32 v200, v200, v178
	v_exp_f32_e32 v182, v182
	v_add_f32_e32 v200, v200, v179
	v_cvt_pk_bf16_f32 v177, v178, v179
	v_exp_f32_e32 v183, v183
	v_add_f32_e32 v200, v200, v180
	v_add_f32_e32 v200, v200, v181
	v_cvt_pk_bf16_f32 v178, v180, v181
	v_add_f32_e32 v200, v200, v182
	v_add_f32_e32 v200, v200, v183
	v_cvt_pk_bf16_f32 v179, v182, v183
	s_waitcnt lgkmcnt(0)
	ds_read_b64_tr_b16 v[242:243], v204 offset:53248
	ds_read_b64_tr_b16 v[244:245], v205 offset:55296
	ds_read_b64_tr_b16 v[246:247], v204 offset:53760
	ds_read_b64_tr_b16 v[248:249], v205 offset:55808
	ds_read_b64_tr_b16 v[250:251], v204 offset:54272
	ds_read_b64_tr_b16 v[252:253], v205 offset:56320
	ds_read_b64_tr_b16 v[208:209], v204 offset:54784
	ds_read_b64_tr_b16 v[210:211], v205 offset:56832
	v_mfma_f32_32x32x16_bf16 v[96:111], v[226:229], v[160:163], v[96:111]
	v_sub_f32_e32 v184, v184, v198
	v_sub_f32_e32 v185, v185, v198
	v_sub_f32_e32 v186, v186, v198
	v_exp_f32_e32 v184, v184
	v_sub_f32_e32 v187, v187, v198
	v_exp_f32_e32 v185, v185
	v_mfma_f32_32x32x16_bf16 v[64:79], v[230:233], v[160:163], v[64:79]
	v_sub_f32_e32 v188, v188, v198
	v_exp_f32_e32 v186, v186
	v_sub_f32_e32 v189, v189, v198
	v_exp_f32_e32 v187, v187
	v_add_f32_e32 v200, v200, v184
	v_sub_f32_e32 v190, v190, v198
	v_mfma_f32_32x32x16_bf16 v[32:47], v[234:237], v[160:163], v[32:47]
	v_exp_f32_e32 v188, v188
	v_add_f32_e32 v200, v200, v185
	v_sub_f32_e32 v191, v191, v198
	v_cvt_pk_bf16_f32 v180, v184, v185
	v_exp_f32_e32 v189, v189
	v_add_f32_e32 v200, v200, v186
	v_mfma_f32_32x32x16_bf16 v[0:15], v[238:241], v[160:163], v[0:15]
	v_exp_f32_e32 v190, v190
	v_add_f32_e32 v200, v200, v187
	v_cvt_pk_bf16_f32 v181, v186, v187
	v_exp_f32_e32 v191, v191
	v_add_f32_e32 v200, v200, v188
	v_add_f32_e32 v200, v200, v189
	v_mfma_f32_32x32x16_bf16 v[112:127], v[226:229], v[176:179], v[112:127]
	v_cvt_pk_bf16_f32 v182, v188, v189
	v_add_f32_e32 v200, v200, v190
	v_add_f32_e32 v200, v200, v191
	v_cvt_pk_bf16_f32 v183, v190, v191
	v_sub_f32_e32 v128, v128, v199
	v_sub_f32_e32 v129, v129, v199
	v_mfma_f32_32x32x16_bf16 v[80:95], v[230:233], v[176:179], v[80:95]
	v_sub_f32_e32 v130, v130, v199
	v_exp_f32_e32 v128, v128
	v_sub_f32_e32 v131, v131, v199
	v_exp_f32_e32 v129, v129
	v_sub_f32_e32 v132, v132, v199
	v_exp_f32_e32 v130, v130
	v_mfma_f32_32x32x16_bf16 v[48:63], v[234:237], v[176:179], v[48:63]
	v_sub_f32_e32 v133, v133, v199
	v_exp_f32_e32 v131, v131
	v_add_f32_e32 v201, v201, v128
	v_sub_f32_e32 v134, v134, v199
	v_exp_f32_e32 v132, v132
	v_add_f32_e32 v201, v201, v129
	v_mfma_f32_32x32x16_bf16 v[16:31], v[238:241], v[176:179], v[16:31]
	v_sub_f32_e32 v135, v135, v199
	v_cvt_pk_bf16_f32 v168, v128, v129
	v_exp_f32_e32 v133, v133
	v_add_f32_e32 v201, v201, v130
	v_exp_f32_e32 v134, v134
	v_add_f32_e32 v201, v201, v131
	s_waitcnt lgkmcnt(0)
	ds_read_b64_tr_b16 v[226:227], v204 offset:57344
	ds_read_b64_tr_b16 v[228:229], v205 offset:59392
	ds_read_b64_tr_b16 v[230:231], v204 offset:57856
	ds_read_b64_tr_b16 v[232:233], v205 offset:59904
	ds_read_b64_tr_b16 v[234:235], v204 offset:58368
	ds_read_b64_tr_b16 v[236:237], v205 offset:60416
	ds_read_b64_tr_b16 v[238:239], v204 offset:58880
	ds_read_b64_tr_b16 v[240:241], v205 offset:60928
	v_mfma_f32_32x32x16_bf16 v[96:111], v[242:245], v[164:167], v[96:111]
	v_cvt_pk_bf16_f32 v169, v130, v131
	v_exp_f32_e32 v135, v135
	v_add_f32_e32 v201, v201, v132
	v_add_f32_e32 v201, v201, v133
	v_cvt_pk_bf16_f32 v170, v132, v133
	v_add_f32_e32 v201, v201, v134
	v_mfma_f32_32x32x16_bf16 v[64:79], v[246:249], v[164:167], v[64:79]
	v_add_f32_e32 v201, v201, v135
	v_cvt_pk_bf16_f32 v171, v134, v135
	v_sub_f32_e32 v144, v144, v198
	v_sub_f32_e32 v145, v145, v198
	v_sub_f32_e32 v146, v146, v198
	v_exp_f32_e32 v144, v144
	v_mfma_f32_32x32x16_bf16 v[32:47], v[250:253], v[164:167], v[32:47]
	v_sub_f32_e32 v147, v147, v198
	v_exp_f32_e32 v145, v145
	v_sub_f32_e32 v148, v148, v198
	v_exp_f32_e32 v146, v146
	v_sub_f32_e32 v149, v149, v198
	v_mfma_f32_32x32x16_bf16 v[0:15], v[208:211], v[164:167], v[0:15]
	v_exp_f32_e32 v147, v147
	v_add_f32_e32 v200, v200, v144
	v_sub_f32_e32 v150, v150, v198
	v_exp_f32_e32 v148, v148
	v_add_f32_e32 v200, v200, v145
	v_mfma_f32_32x32x16_bf16 v[112:127], v[242:245], v[180:183], v[112:127]
	v_sub_f32_e32 v151, v151, v198
	v_cvt_pk_bf16_f32 v184, v144, v145
	v_exp_f32_e32 v149, v149
	v_add_f32_e32 v200, v200, v146
	v_exp_f32_e32 v150, v150
	v_mfma_f32_32x32x16_bf16 v[80:95], v[246:249], v[180:183], v[80:95]
	v_add_f32_e32 v200, v200, v147
	v_cvt_pk_bf16_f32 v185, v146, v147
	v_exp_f32_e32 v151, v151
	v_add_f32_e32 v200, v200, v148
	v_add_f32_e32 v200, v200, v149
	v_mfma_f32_32x32x16_bf16 v[48:63], v[250:253], v[180:183], v[48:63]
	v_cvt_pk_bf16_f32 v186, v148, v149
	v_add_f32_e32 v200, v200, v150
	v_add_f32_e32 v200, v200, v151
	v_cvt_pk_bf16_f32 v187, v150, v151
	v_sub_f32_e32 v136, v136, v199
	v_mfma_f32_32x32x16_bf16 v[16:31], v[208:211], v[180:183], v[16:31]
	v_sub_f32_e32 v137, v137, v199
	v_sub_f32_e32 v138, v138, v199
	v_exp_f32_e32 v136, v136
	v_sub_f32_e32 v139, v139, v199
	v_exp_f32_e32 v137, v137
	s_waitcnt lgkmcnt(0)
; DI bf16_t* slot(const Params& p, int i) { return (bf16_t*)(p.ws + OFF_SLOT + (size_t)i * SLOT); }
; #define MFMA32(a, b, c) __builtin_amdgcn_mfma_f32_32x32x16_bf16((a), (b), (c), 0, 0, 0)
; #define WAIT_V(n) asm volatile("s_waitcnt vmcnt(" #n ")" ::: "memory")
; #define BAR __builtin_amdgcn_s_barrier()
; #define WAIT_V(n) asm volatile("s_waitcnt vmcnt(" #n ")" ::: "memory")
; #define BAR do { __builtin_amdgcn_sched_barrier(0); __builtin_amdgcn_s_barrier(); asm volatile("" ::: "memory"); __builtin_amdgcn_sched_barrier(0); } while (0)
; DI void dattn_unit2(const bf16_t* __restrict__ Qg, const bf16_t* __restrict__ Kg, const bf16_t* __restrict__ Vg, bf16_t* __restrict__ Og,
;                     int ntiles, int wave_tiles, float lam, const float* __restrict__ gsub, lds_t* shm) {
;     ...
;     for (int ks = 0; ks < 4; ++ks) {
;       bf16x8 vf[NC];
; #pragma unroll
;       for (int c = 0; c < NC; ++c) { const int vo = 512 * c + 4096 * ks; vf[c] = tr_pair(V0 + vo, V1 + vo + 2048); }
; #pragma unroll
;       for (int c = 0; c < NC; ++c) { O[0][c] = MFMA32(vf[c], P[0][ks >> 1][ks & 1], O[0][c]); O[1][c] = MFMA32(vf[c], P[1][ks >> 1][ks & 1], O[1][c]); }
;     }
;     __builtin_amdgcn_sched_barrier(0);
;     WAIT_V(4); BAR;
;     slot = slot == 2 ? 0 : slot + 1;
;   }
	ds_read_b64_tr_b16 v[242:243], v204 offset:61440
	ds_read_b64_tr_b16 v[244:245], v205 offset:63488
	ds_read_b64_tr_b16 v[246:247], v204 offset:61952
	ds_read_b64_tr_b16 v[248:249], v205 offset:64000
	ds_read_b64_tr_b16 v[250:251], v204 offset:62464
	ds_read_b64_tr_b16 v[252:253], v205 offset:64512
	ds_read_b64_tr_b16 v[208:209], v204 offset:62976
	ds_read_b64_tr_b16 v[210:211], v205 offset:65024
	v_mfma_f32_32x32x16_bf16 v[96:111], v[226:229], v[168:171], v[96:111]
	v_sub_f32_e32 v140, v140, v199
	v_exp_f32_e32 v138, v138
	v_sub_f32_e32 v141, v141, v199
	v_exp_f32_e32 v139, v139
	v_add_f32_e32 v201, v201, v136
	v_mfma_f32_32x32x16_bf16 v[64:79], v[230:233], v[168:171], v[64:79]
	v_sub_f32_e32 v142, v142, v199
	v_exp_f32_e32 v140, v140
	v_add_f32_e32 v201, v201, v137
	v_sub_f32_e32 v143, v143, v199
	v_cvt_pk_bf16_f32 v172, v136, v137
	v_mfma_f32_32x32x16_bf16 v[32:47], v[234:237], v[168:171], v[32:47]
	v_exp_f32_e32 v141, v141
	v_add_f32_e32 v201, v201, v138
	v_exp_f32_e32 v142, v142
	v_add_f32_e32 v201, v201, v139
	v_cvt_pk_bf16_f32 v173, v138, v139
	v_mfma_f32_32x32x16_bf16 v[0:15], v[238:241], v[168:171], v[0:15]
	v_exp_f32_e32 v143, v143
	v_add_f32_e32 v201, v201, v140
	v_add_f32_e32 v201, v201, v141
	v_cvt_pk_bf16_f32 v174, v140, v141
	v_add_f32_e32 v201, v201, v142
	v_mfma_f32_32x32x16_bf16 v[112:127], v[226:229], v[184:187], v[112:127]
	v_add_f32_e32 v201, v201, v143
	v_cvt_pk_bf16_f32 v175, v142, v143
	v_sub_f32_e32 v152, v152, v198
	v_sub_f32_e32 v153, v153, v198
	v_sub_f32_e32 v154, v154, v198
	v_mfma_f32_32x32x16_bf16 v[80:95], v[230:233], v[184:187], v[80:95]
	v_exp_f32_e32 v152, v152
	v_sub_f32_e32 v155, v155, v198
	v_exp_f32_e32 v153, v153
	v_sub_f32_e32 v156, v156, v198
	v_exp_f32_e32 v154, v154
	v_mfma_f32_32x32x16_bf16 v[48:63], v[234:237], v[184:187], v[48:63]
	v_sub_f32_e32 v157, v157, v198
	v_exp_f32_e32 v155, v155
	v_add_f32_e32 v200, v200, v152
	v_sub_f32_e32 v158, v158, v198
	v_exp_f32_e32 v156, v156
	v_mfma_f32_32x32x16_bf16 v[16:31], v[238:241], v[184:187], v[16:31]
	v_add_f32_e32 v200, v200, v153
	v_sub_f32_e32 v159, v159, v198
	v_cvt_pk_bf16_f32 v188, v152, v153
	v_exp_f32_e32 v157, v157
	v_add_f32_e32 v200, v200, v154
	s_waitcnt lgkmcnt(0)
	v_mfma_f32_32x32x16_bf16 v[96:111], v[242:245], v[172:175], v[96:111]
	v_exp_f32_e32 v158, v158
	v_add_f32_e32 v200, v200, v155
	v_cvt_pk_bf16_f32 v189, v154, v155
	v_exp_f32_e32 v159, v159
	v_add_f32_e32 v200, v200, v156
	v_mfma_f32_32x32x16_bf16 v[64:79], v[246:249], v[172:175], v[64:79]
	v_add_f32_e32 v200, v200, v157
	v_cvt_pk_bf16_f32 v190, v156, v157
	v_add_f32_e32 v200, v200, v158
	v_add_f32_e32 v200, v200, v159
	v_cvt_pk_bf16_f32 v191, v158, v159
	v_mfma_f32_32x32x16_bf16 v[32:47], v[250:253], v[172:175], v[32:47]
	v_mfma_f32_32x32x16_bf16 v[0:15], v[208:211], v[172:175], v[0:15]
	v_mfma_f32_32x32x16_bf16 v[112:127], v[242:245], v[188:191], v[112:127]
	v_mfma_f32_32x32x16_bf16 v[80:95], v[246:249], v[188:191], v[80:95]
	v_mfma_f32_32x32x16_bf16 v[48:63], v[250:253], v[188:191], v[48:63]
	v_mfma_f32_32x32x16_bf16 v[16:31], v[208:211], v[188:191], v[16:31]
.Lda_w2:
	s_setprio 0
	s_waitcnt vmcnt(4)
	s_barrier
	s_add_i32 s4, s59, 1
	s_cmp_lg_u32 s59, 2
	s_cselect_b32 s59, s4, 0
	s_add_i32 s60, s60, 1
	s_cmp_eq_u32 s58, s60
	s_cbranch_scc0 .LBB0_419
	s_branch .LBB0_423
.Lda_maskA:
	s_mov_b64 s[6:7], -1
	s_mov_b64 s[4:5], -1
	s_branch .Lda_w1
